# dilated core + deferred dequeue wait (atomic result consumed at the end of the unit) + no end-of-unit wait for the L2-touch loads
# speedup vs baseline: 1.0067x; 1.0067x over previous
.LBB0_427:
	s_mov_b64 s[56:57], exec
	v_mbcnt_lo_u32_b32 v0, s56, 0
	v_mbcnt_hi_u32_b32 v0, s57, v0
	v_cmp_eq_u32_e32 vcc, 0, v0
	s_and_saveexec_b64 s[54:55], vcc
	s_cbranch_execz .LBB0_429
	s_bcnt1_i32_b64 s10, s[56:57]
	v_mov_b32_e32 v2, s10
	global_atomic_add v239, v1, v2, s[8:9] offset:256 sc0
.LBB0_429:
	s_or_b64 exec, exec, s[54:55]
	s_or_b64 exec, exec, s[52:53]
	s_cmpk_gt_i32 s19, 0x7f
	s_mov_b64 s[52:53], -1
	s_cbranch_scc0 .LBB0_425

.LBB0_474:
	s_or_b64 exec, exec, s[52:53]
	s_waitcnt lgkmcnt(0)
	s_barrier
	s_branch .LBB0_426

.LBB0_542:
	v_mov_b32_e32 v0, s64
	s_waitcnt vmcnt(0)
	ds_write_b32 v0, v239
	s_branch .LBB0_422

	.amdhsa_kernel _Z8fwd_mega4Args
		.amdhsa_group_segment_fixed_size 0
		.amdhsa_private_segment_fixed_size 0
		.amdhsa_kernarg_size 344
		.amdhsa_user_sgpr_count 2
		.amdhsa_user_sgpr_dispatch_ptr 0
		.amdhsa_user_sgpr_queue_ptr 0
		.amdhsa_user_sgpr_kernarg_segment_ptr 1
		.amdhsa_user_sgpr_dispatch_id 0
		.amdhsa_user_sgpr_kernarg_preload_length 0
		.amdhsa_user_sgpr_kernarg_preload_offset 0
		.amdhsa_user_sgpr_private_segment_size 0
		.amdhsa_uses_dynamic_stack 0
		.amdhsa_enable_private_segment 0
		.amdhsa_system_sgpr_workgroup_id_x 1
		.amdhsa_system_sgpr_workgroup_id_y 0
		.amdhsa_system_sgpr_workgroup_id_z 0
		.amdhsa_system_sgpr_workgroup_info 0
		.amdhsa_system_vgpr_workitem_id 2
		.amdhsa_next_free_vgpr 240
		.amdhsa_next_free_sgpr 100
		.amdhsa_accum_offset 240
		.amdhsa_reserve_vcc 1
		.amdhsa_float_round_mode_32 0
		.amdhsa_float_round_mode_16_64 0
		.amdhsa_float_denorm_mode_32 3
		.amdhsa_float_denorm_mode_16_64 3
		.amdhsa_dx10_clamp 1
		.amdhsa_ieee_mode 1
		.amdhsa_fp16_overflow 0
		.amdhsa_tg_split 0
		.amdhsa_exception_fp_ieee_invalid_op 0
		.amdhsa_exception_fp_denorm_src 0
		.amdhsa_exception_fp_ieee_div_zero 0
		.amdhsa_exception_fp_ieee_overflow 0
		.amdhsa_exception_fp_ieee_underflow 0
		.amdhsa_exception_fp_ieee_inexact 0
		.amdhsa_exception_int_div_zero 0
	.end_amdhsa_kernel

.Lfunc_end0:
	.size	_Z8fwd_mega4Args, .Lfunc_end0-_Z8fwd_mega4Args
	.set _Z8fwd_mega4Args.num_vgpr, 240
	.set _Z8fwd_mega4Args.num_agpr, 0
	.set _Z8fwd_mega4Args.numbered_sgpr, 100
	.set _Z8fwd_mega4Args.num_named_barrier, 0
	.set _Z8fwd_mega4Args.private_seg_size, 0
	.set _Z8fwd_mega4Args.uses_vcc, 1
	.set _Z8fwd_mega4Args.uses_flat_scratch, 0
	.set _Z8fwd_mega4Args.has_dyn_sized_stack, 0
	.set _Z8fwd_mega4Args.has_recursion, 0
	.set _Z8fwd_mega4Args.has_indirect_call, 0

amdhsa.kernels:
  - .agpr_count:     0
    .args:
      - .offset:         0
        .size:           88
        .value_kind:     by_value
      - .offset:         88
        .size:           4
        .value_kind:     hidden_block_count_x
      - .offset:         92
        .size:           4
        .value_kind:     hidden_block_count_y
      - .offset:         96
        .size:           4
        .value_kind:     hidden_block_count_z
      - .offset:         100
        .size:           2
        .value_kind:     hidden_group_size_x
      - .offset:         102
        .size:           2
        .value_kind:     hidden_group_size_y
      - .offset:         104
        .size:           2
        .value_kind:     hidden_group_size_z
      - .offset:         106
        .size:           2
        .value_kind:     hidden_remainder_x
      - .offset:         108
        .size:           2
        .value_kind:     hidden_remainder_y
      - .offset:         110
        .size:           2
        .value_kind:     hidden_remainder_z
      - .offset:         128
        .size:           8
        .value_kind:     hidden_global_offset_x
      - .offset:         136
        .size:           8
        .value_kind:     hidden_global_offset_y
      - .offset:         144
        .size:           8
        .value_kind:     hidden_global_offset_z
      - .offset:         152
        .size:           2
        .value_kind:     hidden_grid_dims
      - .offset:         176
        .size:           8
        .value_kind:     hidden_multigrid_sync_arg
      - .offset:         208
        .size:           4
        .value_kind:     hidden_dynamic_lds_size
    .group_segment_fixed_size: 0
    .kernarg_segment_align: 8
    .kernarg_segment_size: 344
    .language:       OpenCL C
    .language_version:
      - 2
      - 0
    .max_flat_workgroup_size: 512
    .name:           _Z8fwd_mega4Args
    .private_segment_fixed_size: 0
    .sgpr_count:     106
    .sgpr_spill_count: 1
    .symbol:         _Z8fwd_mega4Args.kd
    .uniform_work_group_size: 1
    .uses_dynamic_stack: false
    .vgpr_count:     240
    .vgpr_spill_count: 0
    .wavefront_size: 64
